# v9 + final norm and init_rows loops rewritten by hand (row loads issued together, next row prefetched one iteration ahead, gain loaded once)
# baseline (speedup 1.0000x reference)
; __device__ __forceinline__ int tid_l() { int t = threadIdx.x; asm volatile("" : "+v"(t)); return t; }
; __device__ __forceinline__ unsigned cvt_pk(float lo, float hi) { return pg8::cvt_pk_bf16(lo, hi); }
; __device__ __forceinline__ void init_rows(ArgsP ap) {
;     const int tid_ = tid_l(); const int lane = tid_ & 63, wave = tid_ >> 6;
;     const int gw = blockIdx.x * 8 + wave, NGW = gridDim.x * 8;
;     bf16* xb = (bf16*)(ap->ws + WS_XB); float* rsp = (float*)(ap->ws + WS_RSP);
;     for (int row = gw; row < T; row += NGW) {
;         const f32x4* xr = (const f32x4*)(ap->in[0] + (size_t)row * DM) + lane; u32x2* xbr = (u32x2*)(xb + (size_t)row * DM) + lane; float s = 0.f;
; #pragma unroll
;         for (int jj = 0; jj < 4; ++jj) { const f32x4 v = xr[64 * jj]; u32x2 w; w.x = cvt_pk(v[0], v[1]); w.y = cvt_pk(v[2], v[3]); xbr[64 * jj] = w; s += (v[0] * v[0] + v[1] * v[1]) + (v[2] * v[2] + v[3] * v[3]); }
;         s = wave_sum(s);
;         if (lane < 4) { f32x4 o = {0.f, 0.f, 0.f, 0.f}; if (lane == 0) o[0] = s; *(f32x4*)(rsp + (size_t)row * 16 + 4 * lane) = o; }
;     }
; }
.LBB0_731:
	s_and_b64 vcc, exec, s[4:5]
	s_cbranch_vccz .LBB0_813
	s_cmp_gt_u32 s3, 7
	s_cbranch_scc1 .LBB0_739
	v_mov_b32_e32 v0, v200
	s_movk_i32 s0, 0x4000
	v_ashrrev_i32_e32 v2, 6, v0
	v_add_u32_e32 v4, s74, v2
	v_cmp_gt_i32_e32 vcc, s0, v4
	s_and_saveexec_b64 s[0:1], vcc
	s_cbranch_execz .LBB0_738
	v_and_b32_e32 v10, 63, v0
	v_and_b32_e32 v0, 64, v201
	v_add_u32_e32 v0, 64, v0
	v_xor_b32_e32 v2, 1, v201
	v_cmp_lt_i32_e32 vcc, v2, v0
	s_load_dwordx2 s[8:9], s[62:63], 0x0
	v_ashrrev_i32_e32 v5, 31, v4
	v_cndmask_b32_e32 v2, v201, v2, vcc
	v_lshlrev_b32_e32 v12, 2, v2
	v_xor_b32_e32 v2, 2, v201
	v_cmp_lt_i32_e32 vcc, v2, v0
	v_lshlrev_b64 v[8:9], 11, v[4:5]
	v_cmp_gt_u32_e64 s[4:5], 4, v10
	v_cndmask_b32_e32 v2, v201, v2, vcc
	v_lshlrev_b32_e32 v13, 2, v2
	v_xor_b32_e32 v2, 4, v201
	v_cmp_lt_i32_e32 vcc, v2, v0
	v_cmp_eq_u32_e64 s[6:7], 0, v10
	v_lshl_or_b32 v8, v10, 3, v8
	v_cndmask_b32_e32 v2, v201, v2, vcc
	v_lshlrev_b32_e32 v14, 2, v2
	v_xor_b32_e32 v2, 8, v201
	v_cmp_lt_i32_e32 vcc, v2, v0
	s_nop 1
	v_cndmask_b32_e32 v2, v201, v2, vcc
	v_lshlrev_b32_e32 v15, 2, v2
	v_xor_b32_e32 v2, 16, v201
	v_cmp_lt_i32_e32 vcc, v2, v0
	s_nop 1
	v_cndmask_b32_e32 v2, v201, v2, vcc
	v_lshlrev_b32_e32 v16, 2, v2
	v_xor_b32_e32 v2, 32, v201
	v_cmp_lt_i32_e32 vcc, v2, v0
	s_nop 1
	v_cndmask_b32_e32 v0, v201, v2, vcc
	v_lshlrev_b32_e32 v17, 2, v0
	s_waitcnt lgkmcnt(0)
	v_lshlrev_b64 v[2:3], 6, v[4:5]
	v_lshlrev_b32_e32 v0, 4, v10
	v_lshl_add_u64 v[6:7], v[2:3], 0, v[0:1]
	v_lshlrev_b64 v[2:3], 12, v[4:5]
	v_or_b32_e32 v2, v2, v0
	v_lshl_add_u64 v[2:3], s[8:9], 0, v[2:3]
	s_mov_b64 s[8:9], 0x800
	v_lshl_add_u64 v[10:11], v[2:3], 0, s[8:9]
	v_readfirstlane_b32 s8, v4
	global_load_dwordx4 v[18:21], v[10:11], off offset:-2048
	global_load_dwordx4 v[22:25], v[10:11], off offset:-1024
	global_load_dwordx4 v[26:29], v[10:11], off
	global_load_dwordx4 v[30:33], v[10:11], off offset:1024
	s_waitcnt vmcnt(0)
.Lir_top:
	v_lshl_add_u64 v[2:3], s[76:77], 0, v[8:9]
	s_mov_b32 s2, 0x580000
	v_add_co_u32_e32 v34, vcc, s2, v2
	s_nop 1
	v_addc_co_u32_e32 v35, vcc, 0, v3, vcc
	v_lshl_add_u64 v[44:45], s[76:77], 0, v[6:7]
	s_add_i32 s8, s8, s78
	v_lshl_add_u64 v[6:7], v[6:7], 0, s[50:51]
	v_lshl_add_u64 v[8:9], v[8:9], 0, s[58:59]
	v_lshl_add_u64 v[10:11], v[10:11], 0, s[68:69]
	s_cmp_lt_i32 s8, 0x4000
	s_cbranch_scc0 .Lir_nopf
	global_load_dwordx4 v[48:51], v[10:11], off offset:-2048
	global_load_dwordx4 v[52:55], v[10:11], off offset:-1024
	global_load_dwordx4 v[56:59], v[10:11], off
	global_load_dwordx4 v[60:63], v[10:11], off offset:1024
.Lir_nopf:
	v_cvt_pk_bf16_f32 v2, v18, v19
	v_cvt_pk_bf16_f32 v3, v20, v21
	v_cvt_pk_bf16_f32 v36, v22, v23
	v_cvt_pk_bf16_f32 v37, v24, v25
	v_cvt_pk_bf16_f32 v38, v26, v27
	v_cvt_pk_bf16_f32 v39, v28, v29
	v_cvt_pk_bf16_f32 v40, v30, v31
	v_cvt_pk_bf16_f32 v41, v32, v33
	global_store_dwordx2 v[34:35], v[2:3], off
	global_store_dwordx2 v[34:35], v[36:37], off offset:512
	global_store_dwordx2 v[34:35], v[38:39], off offset:1024
	global_store_dwordx2 v[34:35], v[40:41], off offset:1536
	v_mul_f32_e32 v0, v19, v19
	v_fmac_f32_e32 v0, v18, v18
	v_mul_f32_e32 v42, v21, v21
	v_fmac_f32_e32 v42, v20, v20
	v_add_f32_e32 v0, v0, v42
	v_mul_f32_e32 v42, v23, v23
	v_mul_f32_e32 v43, v25, v25
	v_fmac_f32_e32 v42, v22, v22
	v_fmac_f32_e32 v43, v24, v24
	v_add_f32_e32 v42, v42, v43
	v_add_f32_e32 v0, v0, v42
	v_mul_f32_e32 v42, v27, v27
	v_mul_f32_e32 v43, v29, v29
	v_fmac_f32_e32 v42, v26, v26
	v_fmac_f32_e32 v43, v28, v28
	v_add_f32_e32 v42, v42, v43
	v_add_f32_e32 v0, v0, v42
	v_mul_f32_e32 v42, v31, v31
	v_mul_f32_e32 v43, v33, v33
	v_fmac_f32_e32 v42, v30, v30
	v_fmac_f32_e32 v43, v32, v32
	v_add_f32_e32 v42, v42, v43
	v_add_f32_e32 v0, v0, v42
	ds_bpermute_b32 v42, v12, v0
	s_waitcnt lgkmcnt(0)
	v_add_f32_e32 v0, v0, v42
	ds_bpermute_b32 v42, v13, v0
	s_waitcnt lgkmcnt(0)
	v_add_f32_e32 v0, v0, v42
	ds_bpermute_b32 v42, v14, v0
	s_waitcnt lgkmcnt(0)
	v_add_f32_e32 v0, v0, v42
	ds_bpermute_b32 v42, v15, v0
	s_waitcnt lgkmcnt(0)
	v_add_f32_e32 v0, v0, v42
	ds_bpermute_b32 v42, v16, v0
	s_waitcnt lgkmcnt(0)
	v_add_f32_e32 v0, v0, v42
	ds_bpermute_b32 v42, v17, v0
	s_waitcnt lgkmcnt(0)
	v_add_f32_e32 v0, v0, v42
	s_and_saveexec_b64 s[10:11], s[4:5]
	v_cndmask_b32_e64 v0, 0, v0, s[6:7]
	v_mov_b32_e32 v2, v1
	v_mov_b32_e32 v3, v1
	global_store_dwordx4 v[44:45], v[0:3], off
	s_or_b64 exec, exec, s[10:11]
	s_cmp_lt_i32 s8, 0x4000
	s_cbranch_scc0 .LBB0_738
	s_waitcnt vmcnt(5)
	v_mov_b32_e32 v18, v48
	v_mov_b32_e32 v19, v49
	v_mov_b32_e32 v20, v50
	v_mov_b32_e32 v21, v51
	v_mov_b32_e32 v22, v52
	v_mov_b32_e32 v23, v53
	v_mov_b32_e32 v24, v54
	v_mov_b32_e32 v25, v55
	v_mov_b32_e32 v26, v56
	v_mov_b32_e32 v27, v57
	v_mov_b32_e32 v28, v58
	v_mov_b32_e32 v29, v59
	v_mov_b32_e32 v30, v60
	v_mov_b32_e32 v31, v61
	v_mov_b32_e32 v32, v62
	v_mov_b32_e32 v33, v63
	s_branch .Lir_top

; __device__ __forceinline__ int tid_l() { int t = threadIdx.x; asm volatile("" : "+v"(t)); return t; }
; __device__ __forceinline__ float bf_lo(unsigned u) { return __uint_as_float(u << 16); }
; __device__ __forceinline__ float bf_hi(unsigned u) { return __uint_as_float(u & 0xffff0000u); }
; __device__ __forceinline__ void final_norm(ArgsP ap) {
;     const int tid_ = tid_l(); const int lane = tid_ & 63, wave = tid_ >> 6;
;     const int gw = blockIdx.x * 8 + wave, NGW = gridDim.x * 8;
;     const float* rsp = (const float*)(ap->ws + WS_RSP); const float* g = ap->in[21]; const bf16* xb = (const bf16*)(ap->ws + WS_XB);
;     for (int row = gw; row < T; row += NGW) {
;         float s = (lane < 16) ? rsp[(size_t)row * 16 + lane] : 0.f; s = wave_sum(s);
;         const float rs = rsqrtf(s * (1.0f / DM) + RMS_EPS);
;         f32x4* orow = (f32x4*)(ap->out + (size_t)row * DM) + lane; const f32x4* gr = (const f32x4*)g + lane; const u32x2* xr = (const u32x2*)(xb + (size_t)row * DM) + lane;
; #pragma unroll
;         for (int jj = 0; jj < 4; ++jj) { const u32x2 xv = xr[64 * jj]; const f32x4 gg = gr[64 * jj]; f32x4 v = {bf_lo(xv.x), bf_hi(xv.x), bf_lo(xv.y), bf_hi(xv.y)}; v = v * rs * gg; orow[64 * jj] = v; }
;     }
; }
.LBB0_865:
	s_movk_i32 s0, 0x4000
	v_ashrrev_i32_e32 v0, 6, v200
	v_add_u32_e32 v0, s74, v0
	v_cmp_gt_i32_e32 vcc, s0, v0
	s_and_saveexec_b64 s[0:1], vcc
	s_cbranch_execz .LBB0_870
	s_load_dwordx4 s[4:7], s[70:71], 0xa8
	s_load_dwordx2 s[2:3], s[70:71], 0xb8
	v_readfirstlane_b32 s8, v0
	v_and_b32_e32 v2, 63, v200
	v_cmp_gt_u32_e64 s[12:13], 16, v2
	v_lshlrev_b32_e32 v3, 2, v2
	v_lshlrev_b32_e32 v4, 3, v2
	v_lshlrev_b32_e32 v5, 4, v2
	v_mov_b32_e32 v46, 0x358637bd
	v_xor_b32_e32 v10, 1, v201
	v_xor_b32_e32 v11, 2, v201
	v_xor_b32_e32 v12, 4, v201
	v_xor_b32_e32 v13, 8, v201
	v_xor_b32_e32 v14, 16, v201
	v_xor_b32_e32 v15, 32, v201
	v_lshlrev_b32_e32 v10, 2, v10
	v_lshlrev_b32_e32 v11, 2, v11
	v_lshlrev_b32_e32 v12, 2, v12
	v_lshlrev_b32_e32 v13, 2, v13
	v_lshlrev_b32_e32 v14, 2, v14
	v_lshlrev_b32_e32 v15, 2, v15
	s_waitcnt lgkmcnt(0)
	global_load_dwordx4 v[48:51], v5, s[4:5]
	global_load_dwordx4 v[52:55], v5, s[4:5] offset:1024
	global_load_dwordx4 v[56:59], v5, s[4:5] offset:2048
	global_load_dwordx4 v[60:63], v5, s[4:5] offset:3072
	s_lshl_b32 s14, s8, 6
	s_add_u32 s20, s2, s14
	s_addc_u32 s21, s3, 0
	s_lshl_b32 s14, s8, 11
	s_add_u32 s22, s2, s14
	s_addc_u32 s23, s3, 0
	s_add_u32 s22, s22, 0x580000
	s_addc_u32 s23, s23, 0
	s_lshl_b32 s14, s8, 12
	s_add_u32 s24, s6, s14
	s_addc_u32 s25, s7, 0
	v_mov_b32_e32 v16, 0
	s_mov_b64 exec, s[12:13]
	global_load_dword v16, v3, s[20:21]
	s_mov_b64 exec, -1
	global_load_dwordx2 v[18:19], v4, s[22:23]
	global_load_dwordx2 v[20:21], v4, s[22:23] offset:512
	global_load_dwordx2 v[22:23], v4, s[22:23] offset:1024
	global_load_dwordx2 v[24:25], v4, s[22:23] offset:1536
	s_waitcnt vmcnt(0)
.Lfn_top:
	s_add_i32 s9, s8, s78
	s_cmp_lt_i32 s9, 0x4000
	s_cbranch_scc0 .Lfn_nopf
	s_add_u32 s26, s20, s50
	s_addc_u32 s27, s21, s51
	s_add_u32 s28, s22, s58
	s_addc_u32 s29, s23, s59
	s_add_u32 s30, s24, s68
	s_addc_u32 s31, s25, s69
	v_mov_b32_e32 v17, 0
	s_mov_b64 exec, s[12:13]
	global_load_dword v17, v3, s[26:27]
	s_mov_b64 exec, -1
	global_load_dwordx2 v[26:27], v4, s[28:29]
	global_load_dwordx2 v[28:29], v4, s[28:29] offset:512
	global_load_dwordx2 v[30:31], v4, s[28:29] offset:1024
	global_load_dwordx2 v[32:33], v4, s[28:29] offset:1536
.Lfn_nopf:
	ds_bpermute_b32 v6, v10, v16
	s_waitcnt lgkmcnt(0)
	v_add_f32_e32 v16, v16, v6
	ds_bpermute_b32 v6, v11, v16
	s_waitcnt lgkmcnt(0)
	v_add_f32_e32 v16, v16, v6
	ds_bpermute_b32 v6, v12, v16
	s_waitcnt lgkmcnt(0)
	v_add_f32_e32 v16, v16, v6
	ds_bpermute_b32 v6, v13, v16
	s_waitcnt lgkmcnt(0)
	v_add_f32_e32 v16, v16, v6
	ds_bpermute_b32 v6, v14, v16
	s_waitcnt lgkmcnt(0)
	v_add_f32_e32 v16, v16, v6
	ds_bpermute_b32 v6, v15, v16
	s_waitcnt lgkmcnt(0)
	v_add_f32_e32 v16, v16, v6
	v_fmamk_f32 v16, v16, 0x3a800000, v46
	v_rsq_f32_e32 v44, v16
	v_lshlrev_b32_e32 v34, 16, v18
	v_and_b32_e32 v35, 0xffff0000, v18
	v_lshlrev_b32_e32 v36, 16, v19
	v_and_b32_e32 v37, 0xffff0000, v19
	v_pk_mul_f32 v[34:35], v[44:45], v[34:35] op_sel_hi:[0,1]
	v_pk_mul_f32 v[36:37], v[44:45], v[36:37] op_sel_hi:[0,1]
	v_pk_mul_f32 v[64:65], v[48:49], v[34:35]
	v_pk_mul_f32 v[66:67], v[50:51], v[36:37]
	v_lshlrev_b32_e32 v34, 16, v20
	v_and_b32_e32 v35, 0xffff0000, v20
	v_lshlrev_b32_e32 v36, 16, v21
	v_and_b32_e32 v37, 0xffff0000, v21
	v_pk_mul_f32 v[34:35], v[44:45], v[34:35] op_sel_hi:[0,1]
	v_pk_mul_f32 v[36:37], v[44:45], v[36:37] op_sel_hi:[0,1]
	v_pk_mul_f32 v[68:69], v[52:53], v[34:35]
	v_pk_mul_f32 v[70:71], v[54:55], v[36:37]
	v_lshlrev_b32_e32 v34, 16, v22
	v_and_b32_e32 v35, 0xffff0000, v22
	v_lshlrev_b32_e32 v36, 16, v23
	v_and_b32_e32 v37, 0xffff0000, v23
	v_pk_mul_f32 v[34:35], v[44:45], v[34:35] op_sel_hi:[0,1]
	v_pk_mul_f32 v[36:37], v[44:45], v[36:37] op_sel_hi:[0,1]
	v_pk_mul_f32 v[72:73], v[56:57], v[34:35]
	v_pk_mul_f32 v[74:75], v[58:59], v[36:37]
	v_lshlrev_b32_e32 v34, 16, v24
	v_and_b32_e32 v35, 0xffff0000, v24
	v_lshlrev_b32_e32 v36, 16, v25
	v_and_b32_e32 v37, 0xffff0000, v25
	v_pk_mul_f32 v[34:35], v[44:45], v[34:35] op_sel_hi:[0,1]
	v_pk_mul_f32 v[36:37], v[44:45], v[36:37] op_sel_hi:[0,1]
	v_pk_mul_f32 v[76:77], v[60:61], v[34:35]
	v_pk_mul_f32 v[78:79], v[62:63], v[36:37]
	global_store_dwordx4 v5, v[64:67], s[24:25]
	global_store_dwordx4 v5, v[68:71], s[24:25] offset:1024
	global_store_dwordx4 v5, v[72:75], s[24:25] offset:2048
	global_store_dwordx4 v5, v[76:79], s[24:25] offset:3072
	s_cmp_lt_i32 s9, 0x4000
	s_cbranch_scc0 .LBB0_870
	s_waitcnt vmcnt(4)
	v_mov_b32_e32 v16, v17
	v_mov_b32_e32 v18, v26
	v_mov_b32_e32 v19, v27
	v_mov_b32_e32 v20, v28
	v_mov_b32_e32 v21, v29
	v_mov_b32_e32 v22, v30
	v_mov_b32_e32 v23, v31
	v_mov_b32_e32 v24, v32
	v_mov_b32_e32 v25, v33
	s_mov_b32 s8, s9
	s_mov_b64 s[20:21], s[26:27]
	s_mov_b64 s[22:23], s[28:29]
	s_mov_b64 s[24:25], s[30:31]
	s_branch .Lfn_top
